# strategy 4: static s_setprio 1 for waves 4-7 in the attention and retention-scan phases (reset to 0 at phase end)
# speedup vs baseline: 1.0027x; 1.0027x over previous
; DI int opaque_tid() { int t = threadIdx.x; asm volatile("" : "+v"(t)); return t; }
; DI void ph_attn(const Params& p, bf16_t* smem, int* s_item) {
;     const int tid = opaque_tid(), lane = tid & 63, w = tid >> 6, r = lane & 31, h = lane >> 5;
;     const bf16_t* PQK = (const bf16_t*)(p.ws + OFF_PQK);
;     bf16_t* MIX = (bf16_t*)(p.ws + OFF_HB);
;     const float lam = ((const float*)(p.ws + OFF_MISC))[0];
;     unsigned* ctr = (unsigned*)(p.ws + OFF_CNT);
;     const unsigned* knm = (const unsigned*)(p.ws + OFF_CNT) + 128;
;     constexpr int NQB = 33, NDIFF = NQB * 16, NITEM = NQB * 48;
.LBB0_592:
	s_or_b64 exec, exec, s[0:1]
	s_waitcnt lgkmcnt(0)
	v_mov_b32_e32 v0, v210
	v_mov_b32_e32 v1, 0xfa68000
	s_barrier
	v_readfirstlane_b32 s98, v210
	s_nop 3
	s_cmp_ge_u32 s98, 0x100
	s_cbranch_scc0 .Lprio_skip_3
	s_setprio 1
.Lprio_skip_3:
	global_load_dword v140, v1, s[56:57]
	s_mov_b32 s21, 0
	s_add_u32 s18, s56, 0xfa6d000
	s_mov_b32 s3, s21
	s_addc_u32 s19, s57, 0
	s_lshl_b64 s[4:5], s[2:3], 17
	v_lshrrev_b32_e32 v4, 3, v0
	s_movk_i32 s6, 0xffe0
	v_ashrrev_i32_e32 v3, 1, v0
	v_lshlrev_b32_e32 v2, 6, v0
	v_and_b32_e32 v144, 4, v4
	s_add_u32 s4, s54, s4
	v_mov_b32_e32 v1, 0
	s_mov_b32 s22, 0x54932108
	s_mov_b32 s26, 2.0
	s_mov_b32 s28, 4.0
	s_mov_b32 s48, 0x40c00000
	v_cmp_eq_u32_e64 s[0:1], 0, v0
	v_bfi_b32 v217, s6, v3, v0
	v_ashrrev_i32_e32 v3, 31, v2
	s_addc_u32 s5, s55, s5
	v_lshlrev_b32_e32 v0, 2, v144
	s_add_i32 s3, 0, 0x20400
	s_mov_b32 s23, 0xba76
	s_movk_i32 s25, 0x2010
	s_movk_i32 s77, 0x200f
	s_mov_b32 s79, 0xf800000
	v_mov_b32_e32 v211, 0x260
	s_movk_i32 s88, 0x90
	s_mov_b32 s24, 0x3e38aa3b
	v_mov_b32_e32 v212, 0x3c23d70a
	s_mov_b32 s89, 0xff800000
	s_mov_b32 s27, 0x40400000
	s_mov_b32 s29, 0x40a00000
	s_mov_b32 s49, 0x40e00000
	v_mov_b32_e32 v143, 0xc3180000
	v_mov_b32_e32 v213, 0x358637bd
	v_not_b32_e32 v214, 31
	v_not_b32_e32 v215, 47
	v_mov_b32_e32 v216, 0xff800000
	s_add_i32 s90, 0, 0x1ff00
	v_lshl_add_u64 v[146:147], v[2:3], 2, s[4:5]
	v_lshl_add_u64 v[148:149], s[46:47], 0, v[0:1]
	v_mov_b32_e32 v218, s3
	v_mov_b32_e32 v150, 0x3e38aa3b
	s_waitcnt vmcnt(0)
	v_mov_b32_e32 v141, v140
	s_branch .LBB0_596

; DI int opaque_tid() { int t = threadIdx.x; asm volatile("" : "+v"(t)); return t; }
; DI void xcd_barrier(const XcdBarrier& b) {
;     asm volatile("s_waitcnt vmcnt(0)" ::: "memory");
;     __syncthreads();
;     if (opaque_tid() == 0) {
;         unsigned* bar = b.bar;
;         __builtin_amdgcn_s_waitcnt(0);
;         unsigned nloc = b.st[0], nx = b.st[1];
;         if (nloc == 0u) { xcd_barrier_complete(bar, b.x, nloc, nx); b.st[0] = nloc; b.st[1] = nx; }
.LBB0_726:
	s_waitcnt vmcnt(0)
	v_mov_b32_e32 v0, v210
	s_setprio 0
	s_barrier
	s_nop 0
	v_cmp_eq_u32_e32 vcc, 0, v0
	s_and_saveexec_b64 s[0:1], vcc
	s_cbranch_execz .LBB0_778
	s_add_i32 s3, 0, 0x20600
	v_mov_b32_e32 v0, s3
	s_waitcnt vmcnt(0) expcnt(0) lgkmcnt(0)
	ds_read_b32 v2, v0
	s_add_i32 s3, 0, 0x20604
	v_mov_b32_e32 v0, s3
	ds_read_b32 v0, v0
	s_waitcnt lgkmcnt(1)
	v_cmp_ne_u32_e32 vcc, 0, v2
	s_cbranch_vccnz .LBB0_742
	s_add_u32 s4, s56, 0xfa69200
	s_addc_u32 s5, s57, 0
	s_add_u32 s6, s56, 0xfa69400
	s_addc_u32 s7, s57, 0
	s_add_u32 s8, s56, 0xfa69500
	s_addc_u32 s9, s57, 0
	s_add_u32 s10, s56, 0xfa69600
	s_addc_u32 s11, s57, 0
	s_add_u32 s12, s56, 0xfa69700
	s_addc_u32 s13, s57, 0
	s_add_u32 s14, s56, 0xfa69800
	s_addc_u32 s15, s57, 0
	s_add_u32 s16, s56, 0xfa69900
	s_addc_u32 s17, s57, 0
	s_add_u32 s18, s56, 0xfa69a00
	s_addc_u32 s19, s57, 0
	s_add_u32 s20, s56, 0xfa69b00
	s_addc_u32 s21, s57, 0
	s_add_u32 s22, s56, 0xfa69c00
	s_addc_u32 s23, s57, 0
	s_add_u32 s24, s56, 0xfa69d00
	s_addc_u32 s25, s57, 0
	s_add_u32 s26, s56, 0xfa69e00
	s_addc_u32 s27, s57, 0
	s_add_u32 s28, s56, 0xfa69f00
	s_addc_u32 s29, s57, 0
	s_add_u32 s44, s56, 0xfa6a000
	s_addc_u32 s45, s57, 0
	s_add_u32 s46, s56, 0xfa6a100
	s_addc_u32 s47, s57, 0
	s_add_u32 s48, s56, 0xfa6a200
	v_readlane_b32 s3, v252, 0
	s_addc_u32 s49, s57, 0
	s_mul_i32 s3, s59, s3
	s_add_u32 s50, s56, 0xfa6a300
	s_mul_i32 s3, s3, s58
	s_addc_u32 s51, s57, 0
	s_mov_b32 s35, 1
	v_mov_b32_e32 v16, 0
	s_branch .LBB0_730

; DI void ph_scan(const Params& p) {
;     for (int ub = blockIdx.x; ub < 256; ub += gridDim.x) {
;         const int xcd = ub & 7, j = ub >> 3;
;         scan_block(p, ((xcd * 2 + (j >> 4)) << 4) | (j & 15));
.LBB0_1532:
	s_or_b64 exec, exec, s[6:7]
	s_cmpk_gt_i32 s2, 0xff
	s_waitcnt lgkmcnt(0)
	s_barrier
	s_cbranch_scc1 .LBB0_1566
	v_readfirstlane_b32 s98, v210
	s_nop 3
	s_cmp_ge_u32 s98, 0x100
	s_cbranch_scc0 .Lprio_skip_11
	s_setprio 1
.Lprio_skip_11:
	s_add_u32 s35, s54, 0x4080000
	s_addc_u32 s50, s55, 0
	s_add_u32 s10, s54, 0x50a0000
	s_addc_u32 s11, s55, 0
	s_lshl_b32 s51, s58, 1
	s_mov_b32 s13, 0
	v_mov_b32_e32 v185, 0
	s_mov_b32 s52, 0x800000
	v_mov_b32_e32 v206, 0x42000000
	s_mov_b32 s53, 0x80000
	s_mov_b32 s60, 0x20000
	s_add_i32 s61, 0, 0x21000
	s_movk_i32 s66, 0xffc0
	s_mov_b64 s[14:15], 0x300000
	s_mov_b64 s[22:23], 0x60000
	s_mov_b64 s[26:27], 0x180000
	s_mov_b32 s67, s2
	s_branch .LBB0_1535

; DI int opaque_tid() { int t = threadIdx.x; asm volatile("" : "+v"(t)); return t; }
; DI void xcd_barrier(const XcdBarrier& b) {
;     asm volatile("s_waitcnt vmcnt(0)" ::: "memory");
;     __syncthreads();
;     if (opaque_tid() == 0) {
;         unsigned* bar = b.bar;
;         __builtin_amdgcn_s_waitcnt(0);
;         unsigned nloc = b.st[0], nx = b.st[1];
;         if (nloc == 0u) { xcd_barrier_complete(bar, b.x, nloc, nx); b.st[0] = nloc; b.st[1] = nx; }
.LBB0_1566:
	s_waitcnt vmcnt(0)
	v_mov_b32_e32 v0, v210
	s_setprio 0
	s_barrier
	s_nop 0
	v_cmp_eq_u32_e32 vcc, 0, v0
	s_and_saveexec_b64 s[6:7], vcc
	s_cbranch_execz .LBB0_1618
	s_add_i32 s3, 0, 0x20600
	v_mov_b32_e32 v0, s3
	s_waitcnt vmcnt(0) expcnt(0) lgkmcnt(0)
	ds_read_b32 v2, v0
	s_add_i32 s3, 0, 0x20604
	v_mov_b32_e32 v0, s3
	ds_read_b32 v0, v0
	s_waitcnt lgkmcnt(1)
	v_cmp_ne_u32_e32 vcc, 0, v2
	s_cbranch_vccnz .LBB0_1582
	s_add_u32 s8, s56, 0xfa69200
	s_addc_u32 s9, s57, 0
	s_add_u32 s10, s56, 0xfa69400
	s_addc_u32 s11, s57, 0
	s_add_u32 s12, s56, 0xfa69500
	s_addc_u32 s13, s57, 0
	s_add_u32 s14, s56, 0xfa69600
	s_addc_u32 s15, s57, 0
	s_add_u32 s22, s56, 0xfa69700
	s_addc_u32 s23, s57, 0
	s_add_u32 s24, s56, 0xfa69800
	s_addc_u32 s25, s57, 0
	s_add_u32 s26, s56, 0xfa69900
	s_addc_u32 s27, s57, 0
	s_add_u32 s28, s56, 0xfa69a00
	s_addc_u32 s29, s57, 0
	s_add_u32 s44, s56, 0xfa69b00
	s_addc_u32 s45, s57, 0
	s_add_u32 s46, s56, 0xfa69c00
	s_addc_u32 s47, s57, 0
	s_add_u32 s48, s56, 0xfa69d00
	s_addc_u32 s49, s57, 0
	s_add_u32 s50, s56, 0xfa69e00
	s_addc_u32 s51, s57, 0
	s_add_u32 s52, s56, 0xfa69f00
	s_addc_u32 s53, s57, 0
	s_add_u32 s60, s56, 0xfa6a000
	s_addc_u32 s61, s57, 0
	s_add_u32 s66, s56, 0xfa6a100
	s_addc_u32 s67, s57, 0
	s_add_u32 s68, s56, 0xfa6a200
	v_readlane_b32 s3, v252, 0
	s_addc_u32 s69, s57, 0
	s_mul_i32 s3, s59, s3
	s_add_u32 s70, s56, 0xfa6a300
	s_mul_i32 s3, s3, s58
	s_addc_u32 s71, s57, 0
	s_mov_b32 s35, 1
	v_mov_b32_e32 v16, 0
	s_branch .LBB0_1570

; DI int opaque_tid() { int t = threadIdx.x; asm volatile("" : "+v"(t)); return t; }
; #define LAS __attribute__((address_space(3)))
; #define PHS(N) run_phase<N>(p, smem, s_aux); xcd_barrier(xb);
; __global__ void __launch_bounds__(512, 2) k_mega(Params p) {
;     bf16_t* smem = (bf16_t*)dsm;
;     float* s_aux = (float*)(dsm + SMEM_BYTES);
;     uint4* xbw = (uint4*)(dsm + SMEM_BYTES + 1536);
;     cg::grid_group grid = cg::this_grid();
;     if (opaque_tid() == 0) *xbw = make_uint4(0u, 0u, 0u, 0u);
;     __syncthreads();
;     const XcdBarrier xb = xcd_barrier_post((unsigned*)(p.ws + OFF_BAR), (volatile LAS unsigned*)xbw);
;     if (p.ws == nullptr) grid.sync();
;     ...
;     PHS(0) PHS(1) PHS(2) PHS(3) PHS(4) PHS(5) PHS(6) PHS(7) PHS(8) PHS(9) PHS(10) PHS(11) PHS(12) PHS(13) PHS(14) PHS(15) PHS(16)
;     run_phase<17>(p, smem, s_aux);
; }
	.amdhsa_kernel _Z6k_mega6Params
		.amdhsa_group_segment_fixed_size 0
		.amdhsa_private_segment_fixed_size 0
		.amdhsa_kernarg_size 376
		.amdhsa_user_sgpr_count 2
		.amdhsa_user_sgpr_dispatch_ptr 0
		.amdhsa_user_sgpr_queue_ptr 0
		.amdhsa_user_sgpr_kernarg_segment_ptr 1
		.amdhsa_user_sgpr_dispatch_id 0
		.amdhsa_user_sgpr_kernarg_preload_length 0
		.amdhsa_user_sgpr_kernarg_preload_offset 0
		.amdhsa_user_sgpr_private_segment_size 0
		.amdhsa_uses_dynamic_stack 0
		.amdhsa_enable_private_segment 0
		.amdhsa_system_sgpr_workgroup_id_x 1
		.amdhsa_system_sgpr_workgroup_id_y 0
		.amdhsa_system_sgpr_workgroup_id_z 0
		.amdhsa_system_sgpr_workgroup_info 0
		.amdhsa_system_vgpr_workitem_id 2
		.amdhsa_next_free_vgpr 253
		.amdhsa_next_free_sgpr 102
		.amdhsa_accum_offset 256
		.amdhsa_reserve_vcc 1
		.amdhsa_float_round_mode_32 0
		.amdhsa_float_round_mode_16_64 0
		.amdhsa_float_denorm_mode_32 3
		.amdhsa_float_denorm_mode_16_64 3
		.amdhsa_dx10_clamp 1
		.amdhsa_ieee_mode 1
		.amdhsa_fp16_overflow 0
		.amdhsa_tg_split 0
		.amdhsa_exception_fp_ieee_invalid_op 0
		.amdhsa_exception_fp_denorm_src 0
		.amdhsa_exception_fp_ieee_div_zero 0
		.amdhsa_exception_fp_ieee_overflow 0
		.amdhsa_exception_fp_ieee_underflow 0
		.amdhsa_exception_fp_ieee_inexact 0
		.amdhsa_exception_int_div_zero 0
	.end_amdhsa_kernel

; DI int opaque_tid() { int t = threadIdx.x; asm volatile("" : "+v"(t)); return t; }
; #define LAS __attribute__((address_space(3)))
; #define PHS(N) run_phase<N>(p, smem, s_aux); xcd_barrier(xb);
; __global__ void __launch_bounds__(512, 2) k_mega(Params p) {
;     bf16_t* smem = (bf16_t*)dsm;
;     float* s_aux = (float*)(dsm + SMEM_BYTES);
;     uint4* xbw = (uint4*)(dsm + SMEM_BYTES + 1536);
;     cg::grid_group grid = cg::this_grid();
;     if (opaque_tid() == 0) *xbw = make_uint4(0u, 0u, 0u, 0u);
;     __syncthreads();
;     const XcdBarrier xb = xcd_barrier_post((unsigned*)(p.ws + OFF_BAR), (volatile LAS unsigned*)xbw);
;     if (p.ws == nullptr) grid.sync();
;     ...
;     PHS(0) PHS(1) PHS(2) PHS(3) PHS(4) PHS(5) PHS(6) PHS(7) PHS(8) PHS(9) PHS(10) PHS(11) PHS(12) PHS(13) PHS(14) PHS(15) PHS(16)
;     run_phase<17>(p, smem, s_aux);
; }
amdhsa.kernels:
  - .agpr_count:     0
    .args:
      - .offset:         0
        .size:           120
        .value_kind:     by_value
      - .offset:         120
        .size:           4
        .value_kind:     hidden_block_count_x
      - .offset:         124
        .size:           4
        .value_kind:     hidden_block_count_y
      - .offset:         128
        .size:           4
        .value_kind:     hidden_block_count_z
      - .offset:         132
        .size:           2
        .value_kind:     hidden_group_size_x
      - .offset:         134
        .size:           2
        .value_kind:     hidden_group_size_y
      - .offset:         136
        .size:           2
        .value_kind:     hidden_group_size_z
      - .offset:         138
        .size:           2
        .value_kind:     hidden_remainder_x
      - .offset:         140
        .size:           2
        .value_kind:     hidden_remainder_y
      - .offset:         142
        .size:           2
        .value_kind:     hidden_remainder_z
      - .offset:         160
        .size:           8
        .value_kind:     hidden_global_offset_x
      - .offset:         168
        .size:           8
        .value_kind:     hidden_global_offset_y
      - .offset:         176
        .size:           8
        .value_kind:     hidden_global_offset_z
      - .offset:         184
        .size:           2
        .value_kind:     hidden_grid_dims
      - .offset:         208
        .size:           8
        .value_kind:     hidden_multigrid_sync_arg
      - .offset:         240
        .size:           4
        .value_kind:     hidden_dynamic_lds_size
    .group_segment_fixed_size: 0
    .kernarg_segment_align: 8
    .kernarg_segment_size: 376
    .language:       OpenCL C
    .language_version:
      - 2
      - 0
    .max_flat_workgroup_size: 512
    .name:           _Z6k_mega6Params
    .private_segment_fixed_size: 0
    .sgpr_count:     108
    .sgpr_spill_count: 4
    .symbol:         _Z6k_mega6Params.kd
    .uniform_work_group_size: 1
    .uses_dynamic_stack: false
    .vgpr_count:     253
    .vgpr_spill_count: 0
    .wavefront_size: 64
